# k30 + s_setprio 1/0 flips around the MFMA bursts (QK, PV) of the MLA two-tile blocks
# speedup vs baseline: 1.0069x; 1.0007x over previous
; template <int DQK, int DV, int MODE, int QPRE, bool DIFF> ...
;     ...
;             if (!QKFIRST) {
;                 const LAS unsigned char* kb = lds + bi * BUF + l32 * KST + hi * 16;
;             {
;                 const bf16x8 a0 = *(const LAS bf16x8*)(kb), a1 = *(const LAS bf16x8*)(kb + 32 * KST);
;                 if (MODE == 1) { const f32x16 z16 = {0.f, 0.f, 0.f, 0.f, 0.f, 0.f, 0.f, 0.f, 0.f, 0.f, 0.f, 0.f, 0.f, 0.f, 0.f, 0.f};
;                     s0 = __builtin_amdgcn_mfma_f32_32x32x16_bf16(a0, qf[0], z16, 0, 0, 0); s1 = __builtin_amdgcn_mfma_f32_32x32x16_bf16(a1, qf[0], z16, 0, 0, 0); }
;                 else { s0 = __builtin_amdgcn_mfma_f32_32x32x16_bf16(a0, qf[0], negm, 0, 0, 0); s1 = __builtin_amdgcn_mfma_f32_32x32x16_bf16(a1, qf[0], negm, 0, 0, 0); }
;             }
; #pragma unroll
;             for (int d0 = 1; d0 < ND0; ++d0) {
;                 const bf16x8 a0 = *(const LAS bf16x8*)(kb + d0 * 32), a1 = *(const LAS bf16x8*)(kb + 32 * KST + d0 * 32);
;                 s0 = __builtin_amdgcn_mfma_f32_32x32x16_bf16(a0, qf[d0], s0, 0, 0, 0);
;                 s1 = __builtin_amdgcn_mfma_f32_32x32x16_bf16(a1, qf[d0], s1, 0, 0, 0);
;             }
;             }
;             bf16x8 vf[2][4];
;     ...
;             ATT_LOADV(vf[0], 0); if (!DEEP) ATT_LOADV(vf[1], 1);
;             __builtin_amdgcn_sched_barrier(0);
;             if (MODE != 1) {
;                 float mx = fmaxf(s0[0], s1[0]);
; #pragma unroll
;                 for (int r = 1; r < 16; ++r) mx = fmaxf(fmaxf(mx, s0[r]), s1[r]);
;                 { float a, b; swap32(mx, a, b); mx = fmaxf(a, b); }
;                 const bool first = (i == 0);
;                 if (first || __any(mx > 8.0f)) {
;                     const float dl = first ? mx : fmaxf(mx, 0.f);
;                     mhat += dl;
; #pragma unroll
;                     for (int r = 0; r < 16; ++r) { s0[r] -= dl; s1[r] -= dl; negm[r] = -mhat; }
;                     if (DEEP && QKFIRST && hf == 0 && (ATT_TILE(i0 + UNR - 1) <= my_last)) {
; #pragma unroll
;                         for (int r = 0; r < 16; ++r) { sq[UNR - 1][0][r] -= dl; sq[UNR - 1][1][r] -= dl; }
;                     }
;                     if (!first) {
;                         const float alpha = __builtin_amdgcn_exp2f(-dl);
;                         l_run *= alpha;
; #pragma unroll
;                         for (int i2 = 0; i2 < NDB; ++i2)
; #pragma unroll
.Lmla_pair0:
	ds_read_b128 v[152:155], v195
	ds_read_b128 v[156:159], v195 offset:6656
	ds_read_b128 v[160:163], v195 offset:32
	ds_read_b128 v[164:167], v195 offset:6688
	ds_read_b128 v[236:239], v195 offset:64
	ds_read_b128 v[240:243], v195 offset:6720
	s_setprio 1
	s_waitcnt lgkmcnt(5)
	v_mfma_f32_32x32x16_bf16 v[48:63], v[152:155], v[128:131], v[32:47]
	ds_read_b128 v[244:247], v195 offset:96
	s_waitcnt lgkmcnt(5)
	v_mfma_f32_32x32x16_bf16 v[64:79], v[156:159], v[128:131], v[32:47]
	ds_read_b128 v[248:251], v195 offset:6752
	s_waitcnt lgkmcnt(5)
	v_mfma_f32_32x32x16_bf16 v[48:63], v[160:163], v[132:135], v[48:63]
	ds_read_b128 v[152:155], v195 offset:128
	s_waitcnt lgkmcnt(5)
	v_mfma_f32_32x32x16_bf16 v[64:79], v[164:167], v[132:135], v[64:79]
	ds_read_b128 v[156:159], v195 offset:6784
	s_waitcnt lgkmcnt(5)
	v_mfma_f32_32x32x16_bf16 v[48:63], v[236:239], v[136:139], v[48:63]
	ds_read_b128 v[160:163], v195 offset:160
	s_waitcnt lgkmcnt(5)
	v_mfma_f32_32x32x16_bf16 v[64:79], v[240:243], v[136:139], v[64:79]
	ds_read_b128 v[164:167], v195 offset:6816
	s_waitcnt lgkmcnt(5)
	v_mfma_f32_32x32x16_bf16 v[48:63], v[244:247], v[140:143], v[48:63]
	ds_read_b128 v[236:239], v198 offset:13312
	s_waitcnt lgkmcnt(5)
	v_mfma_f32_32x32x16_bf16 v[64:79], v[248:251], v[140:143], v[64:79]
	ds_read_b128 v[240:243], v198 offset:17920
	s_waitcnt lgkmcnt(5)
	v_mfma_f32_32x32x16_bf16 v[48:63], v[152:155], v[144:147], v[48:63]
	ds_read_b128 v[244:247], v198 offset:13344
	s_waitcnt lgkmcnt(5)
	v_mfma_f32_32x32x16_bf16 v[64:79], v[156:159], v[144:147], v[64:79]
	ds_read_b128 v[248:251], v198 offset:17952
	s_waitcnt lgkmcnt(5)
	v_mfma_f32_32x32x16_bf16 v[48:63], v[160:163], v[148:151], v[48:63]
	ds_read_b128 v[152:155], v198 offset:13376
	s_waitcnt lgkmcnt(5)
	v_mfma_f32_32x32x16_bf16 v[64:79], v[164:167], v[148:151], v[64:79]
	ds_read_b128 v[156:159], v198 offset:17984
	s_setprio 0
	s_nop 6
	v_max3_f32 v199, v48, v49, v50
	s_nop 1
	v_max3_f32 v252, v64, v65, v66
	v_max3_f32 v199, v199, v51, v52
	v_max3_f32 v252, v252, v67, v68
	v_max3_f32 v199, v199, v53, v54
	v_max3_f32 v252, v252, v69, v70
	v_max3_f32 v199, v199, v55, v56
	v_max3_f32 v252, v252, v71, v72
	v_max3_f32 v199, v199, v57, v58
	v_max3_f32 v252, v252, v73, v74
	v_max3_f32 v199, v199, v59, v60
	v_max3_f32 v252, v252, v75, v76
	v_max3_f32 v199, v199, v61, v62
	v_max3_f32 v252, v252, v77, v78
	v_max3_f32 v199, v199, v63, v79
	v_max_f32_e32 v199, v199, v252
	v_mov_b32_e32 v252, v199
	s_nop 1
	v_permlane32_swap_b32_e32 v199, v252
	v_max_f32_e32 v199, v199, v252
	s_cmp_eq_u32 s57, 0
	s_cbranch_scc1 .Lmla_rare0a
	v_cmp_lt_f32_e32 vcc, s51, v199
	s_cbranch_vccnz .Lmla_rare0a
.Lmla_back0a:
	v_exp_f32_e32 v48, v48
	v_exp_f32_e32 v49, v49
	v_exp_f32_e32 v50, v50
	v_add_f32_e32 v252, v48, v49
	v_exp_f32_e32 v51, v51
	v_add_f32_e32 v252, v252, v50
	v_exp_f32_e32 v52, v52
	v_add_f32_e32 v252, v252, v51
	v_exp_f32_e32 v53, v53
	v_add_f32_e32 v252, v252, v52
	v_exp_f32_e32 v54, v54
	v_add_f32_e32 v252, v252, v53
	v_exp_f32_e32 v55, v55
	v_add_f32_e32 v252, v252, v54
	v_add_f32_e32 v252, v252, v55
	v_cvt_pk_bf16_f32 v48, v48, v49
	v_cvt_pk_bf16_f32 v49, v50, v51
	v_cvt_pk_bf16_f32 v50, v52, v53
	v_cvt_pk_bf16_f32 v51, v54, v55
	v_exp_f32_e32 v56, v56
	v_exp_f32_e32 v57, v57
	v_exp_f32_e32 v58, v58
	v_add_f32_e32 v252, v252, v56
	v_exp_f32_e32 v59, v59
	v_add_f32_e32 v252, v252, v57
	v_exp_f32_e32 v60, v60
	v_add_f32_e32 v252, v252, v58
	v_exp_f32_e32 v61, v61
	v_add_f32_e32 v252, v252, v59
	v_exp_f32_e32 v62, v62
	v_add_f32_e32 v252, v252, v60
	v_exp_f32_e32 v63, v63
	v_add_f32_e32 v252, v252, v61
	v_add_f32_e32 v252, v252, v62
	v_add_f32_e32 v252, v252, v63
	v_cvt_pk_bf16_f32 v52, v56, v57
	v_cvt_pk_bf16_f32 v53, v58, v59
	v_cvt_pk_bf16_f32 v54, v60, v61
	v_cvt_pk_bf16_f32 v55, v62, v63
	v_exp_f32_e32 v64, v64
	v_exp_f32_e32 v65, v65
	v_exp_f32_e32 v66, v66
	v_add_f32_e32 v253, v64, v65
	v_exp_f32_e32 v67, v67
	v_add_f32_e32 v253, v253, v66
	v_exp_f32_e32 v68, v68
	v_add_f32_e32 v253, v253, v67
	v_exp_f32_e32 v69, v69
	v_add_f32_e32 v253, v253, v68
	v_exp_f32_e32 v70, v70
	v_add_f32_e32 v253, v253, v69
	v_exp_f32_e32 v71, v71
	v_add_f32_e32 v253, v253, v70
	v_add_f32_e32 v253, v253, v71
	v_cvt_pk_bf16_f32 v56, v64, v65
	v_cvt_pk_bf16_f32 v57, v66, v67
	v_cvt_pk_bf16_f32 v58, v68, v69
	v_cvt_pk_bf16_f32 v59, v70, v71
	v_exp_f32_e32 v72, v72
	v_exp_f32_e32 v73, v73
	v_exp_f32_e32 v74, v74
	v_add_f32_e32 v253, v253, v72
	v_exp_f32_e32 v75, v75
	v_add_f32_e32 v253, v253, v73
	v_exp_f32_e32 v76, v76
	v_add_f32_e32 v253, v253, v74
	v_exp_f32_e32 v77, v77
	v_add_f32_e32 v253, v253, v75
	v_exp_f32_e32 v78, v78
	v_add_f32_e32 v253, v253, v76
	v_exp_f32_e32 v79, v79
	v_add_f32_e32 v253, v253, v77
	v_add_f32_e32 v253, v253, v78
	v_add_f32_e32 v253, v253, v79
	v_cvt_pk_bf16_f32 v60, v72, v73
	v_cvt_pk_bf16_f32 v61, v74, v75
	v_cvt_pk_bf16_f32 v62, v76, v77
	v_cvt_pk_bf16_f32 v63, v78, v79
	v_add_f32_e32 v252, v252, v253
	v_add_f32_e32 v196, v196, v252
	s_setprio 1
	s_waitcnt lgkmcnt(5)
	v_mfma_f32_32x32x16_bf16 v[16:31], v[236:239], v[48:51], v[16:31]
	ds_read_b128 v[160:163], v198 offset:13408
	s_waitcnt lgkmcnt(5)
	v_mfma_f32_32x32x16_bf16 v[0:15], v[240:243], v[48:51], v[0:15]
	ds_read_b128 v[164:167], v198 offset:18016
	s_waitcnt lgkmcnt(5)
	v_mfma_f32_32x32x16_bf16 v[16:31], v[244:247], v[52:55], v[16:31]
	ds_read_b128 v[236:239], v195 offset:22528
	s_waitcnt lgkmcnt(5)
	v_mfma_f32_32x32x16_bf16 v[0:15], v[248:251], v[52:55], v[0:15]
	ds_read_b128 v[240:243], v195 offset:29184
	s_waitcnt lgkmcnt(5)
	v_mfma_f32_32x32x16_bf16 v[16:31], v[152:155], v[56:59], v[16:31]
	ds_read_b128 v[244:247], v195 offset:22560
	s_waitcnt lgkmcnt(5)
; template <int DQK, int DV, int MODE, int QPRE, bool DIFF> ...
;     ...
;             if (!QKFIRST) {
;                 const LAS unsigned char* kb = lds + bi * BUF + l32 * KST + hi * 16;
;             {
;                 const bf16x8 a0 = *(const LAS bf16x8*)(kb), a1 = *(const LAS bf16x8*)(kb + 32 * KST);
;                 if (MODE == 1) { const f32x16 z16 = {0.f, 0.f, 0.f, 0.f, 0.f, 0.f, 0.f, 0.f, 0.f, 0.f, 0.f, 0.f, 0.f, 0.f, 0.f, 0.f};
;                     s0 = __builtin_amdgcn_mfma_f32_32x32x16_bf16(a0, qf[0], z16, 0, 0, 0); s1 = __builtin_amdgcn_mfma_f32_32x32x16_bf16(a1, qf[0], z16, 0, 0, 0); }
;                 else { s0 = __builtin_amdgcn_mfma_f32_32x32x16_bf16(a0, qf[0], negm, 0, 0, 0); s1 = __builtin_amdgcn_mfma_f32_32x32x16_bf16(a1, qf[0], negm, 0, 0, 0); }
;             }
; #pragma unroll
;             for (int d0 = 1; d0 < ND0; ++d0) {
;                 const bf16x8 a0 = *(const LAS bf16x8*)(kb + d0 * 32), a1 = *(const LAS bf16x8*)(kb + 32 * KST + d0 * 32);
;                 s0 = __builtin_amdgcn_mfma_f32_32x32x16_bf16(a0, qf[d0], s0, 0, 0, 0);
;                 s1 = __builtin_amdgcn_mfma_f32_32x32x16_bf16(a1, qf[d0], s1, 0, 0, 0);
;             }
;             }
;             bf16x8 vf[2][4];
;     ...
;             ATT_LOADV(vf[0], 0); if (!DEEP) ATT_LOADV(vf[1], 1);
;             __builtin_amdgcn_sched_barrier(0);
;             if (MODE != 1) {
;                 float mx = fmaxf(s0[0], s1[0]);
; #pragma unroll
;                 for (int r = 1; r < 16; ++r) mx = fmaxf(fmaxf(mx, s0[r]), s1[r]);
;                 { float a, b; swap32(mx, a, b); mx = fmaxf(a, b); }
;                 const bool first = (i == 0);
;                 if (first || __any(mx > 8.0f)) {
;                     const float dl = first ? mx : fmaxf(mx, 0.f);
;                     mhat += dl;
; #pragma unroll
;                     for (int r = 0; r < 16; ++r) { s0[r] -= dl; s1[r] -= dl; negm[r] = -mhat; }
;                     if (DEEP && QKFIRST && hf == 0 && (ATT_TILE(i0 + UNR - 1) <= my_last)) {
; #pragma unroll
;                         for (int r = 0; r < 16; ++r) { sq[UNR - 1][0][r] -= dl; sq[UNR - 1][1][r] -= dl; }
;                     }
;                     if (!first) {
;                         const float alpha = __builtin_amdgcn_exp2f(-dl);
;                         l_run *= alpha;
; #pragma unroll
;                         for (int i2 = 0; i2 < NDB; ++i2)
; #pragma unroll
	v_mfma_f32_32x32x16_bf16 v[0:15], v[156:159], v[56:59], v[0:15]
	ds_read_b128 v[248:251], v195 offset:29216
	s_waitcnt lgkmcnt(5)
	v_mfma_f32_32x32x16_bf16 v[16:31], v[160:163], v[60:63], v[16:31]
	ds_read_b128 v[152:155], v195 offset:22592
	s_waitcnt lgkmcnt(5)
	v_mfma_f32_32x32x16_bf16 v[0:15], v[164:167], v[60:63], v[0:15]
	ds_read_b128 v[156:159], v195 offset:29248
	s_waitcnt lgkmcnt(5)
	v_mfma_f32_32x32x16_bf16 v[204:219], v[236:239], v[128:131], v[32:47]
	ds_read_b128 v[160:163], v195 offset:22624
	s_waitcnt lgkmcnt(5)
	v_mfma_f32_32x32x16_bf16 v[220:235], v[240:243], v[128:131], v[32:47]
	ds_read_b128 v[164:167], v195 offset:29280
	s_waitcnt lgkmcnt(5)
	v_mfma_f32_32x32x16_bf16 v[204:219], v[244:247], v[132:135], v[204:219]
	ds_read_b128 v[236:239], v195 offset:22656
	s_waitcnt lgkmcnt(5)
	v_mfma_f32_32x32x16_bf16 v[220:235], v[248:251], v[132:135], v[220:235]
	ds_read_b128 v[240:243], v195 offset:29312
	s_waitcnt lgkmcnt(5)
	v_mfma_f32_32x32x16_bf16 v[204:219], v[152:155], v[136:139], v[204:219]
	ds_read_b128 v[244:247], v195 offset:22688
	s_waitcnt lgkmcnt(5)
	v_mfma_f32_32x32x16_bf16 v[220:235], v[156:159], v[136:139], v[220:235]
	ds_read_b128 v[248:251], v195 offset:29344
	s_waitcnt lgkmcnt(5)
	v_mfma_f32_32x32x16_bf16 v[204:219], v[160:163], v[140:143], v[204:219]
	ds_read_b128 v[152:155], v198 offset:35840
	s_waitcnt lgkmcnt(5)
	v_mfma_f32_32x32x16_bf16 v[220:235], v[164:167], v[140:143], v[220:235]
	ds_read_b128 v[156:159], v198 offset:40448
	s_waitcnt lgkmcnt(5)
	v_mfma_f32_32x32x16_bf16 v[204:219], v[236:239], v[144:147], v[204:219]
	ds_read_b128 v[160:163], v198 offset:35872
	s_waitcnt lgkmcnt(5)
	v_mfma_f32_32x32x16_bf16 v[220:235], v[240:243], v[144:147], v[220:235]
	ds_read_b128 v[164:167], v198 offset:40480
	s_waitcnt lgkmcnt(5)
	v_mfma_f32_32x32x16_bf16 v[204:219], v[244:247], v[148:151], v[204:219]
	ds_read_b128 v[236:239], v198 offset:35904
	s_waitcnt lgkmcnt(5)
	v_mfma_f32_32x32x16_bf16 v[220:235], v[248:251], v[148:151], v[220:235]
	ds_read_b128 v[240:243], v198 offset:40512
	s_setprio 0
	s_nop 6
	v_max3_f32 v199, v204, v205, v206
	s_nop 1
	v_max3_f32 v252, v220, v221, v222
	v_max3_f32 v199, v199, v207, v208
	v_max3_f32 v252, v252, v223, v224
	v_max3_f32 v199, v199, v209, v210
	v_max3_f32 v252, v252, v225, v226
	v_max3_f32 v199, v199, v211, v212
	v_max3_f32 v252, v252, v227, v228
	v_max3_f32 v199, v199, v213, v214
	v_max3_f32 v252, v252, v229, v230
	v_max3_f32 v199, v199, v215, v216
	v_max3_f32 v252, v252, v231, v232
	v_max3_f32 v199, v199, v217, v218
	v_max3_f32 v252, v252, v233, v234
	v_max3_f32 v199, v199, v219, v235
	v_max_f32_e32 v199, v199, v252
	v_mov_b32_e32 v252, v199
	s_nop 1
	v_permlane32_swap_b32_e32 v199, v252
	v_max_f32_e32 v199, v199, v252
	v_cmp_lt_f32_e32 vcc, s51, v199
	s_cbranch_vccnz .Lmla_rare0b
.Lmla_back0b:
	v_exp_f32_e32 v204, v204
	v_exp_f32_e32 v205, v205
	v_exp_f32_e32 v206, v206
	v_add_f32_e32 v252, v204, v205
	v_exp_f32_e32 v207, v207
	v_add_f32_e32 v252, v252, v206
	v_exp_f32_e32 v208, v208
	v_add_f32_e32 v252, v252, v207
	v_exp_f32_e32 v209, v209
	v_add_f32_e32 v252, v252, v208
	v_exp_f32_e32 v210, v210
	v_add_f32_e32 v252, v252, v209
	v_exp_f32_e32 v211, v211
	v_add_f32_e32 v252, v252, v210
	v_add_f32_e32 v252, v252, v211
	v_cvt_pk_bf16_f32 v204, v204, v205
	v_cvt_pk_bf16_f32 v205, v206, v207
	v_cvt_pk_bf16_f32 v206, v208, v209
	v_cvt_pk_bf16_f32 v207, v210, v211
	v_exp_f32_e32 v212, v212
	v_exp_f32_e32 v213, v213
	v_exp_f32_e32 v214, v214
	v_add_f32_e32 v252, v252, v212
	v_exp_f32_e32 v215, v215
	v_add_f32_e32 v252, v252, v213
	v_exp_f32_e32 v216, v216
	v_add_f32_e32 v252, v252, v214
	v_exp_f32_e32 v217, v217
	v_add_f32_e32 v252, v252, v215
	v_exp_f32_e32 v218, v218
	v_add_f32_e32 v252, v252, v216
	v_exp_f32_e32 v219, v219
	v_add_f32_e32 v252, v252, v217
	v_add_f32_e32 v252, v252, v218
	v_add_f32_e32 v252, v252, v219
	v_cvt_pk_bf16_f32 v208, v212, v213
	v_cvt_pk_bf16_f32 v209, v214, v215
	v_cvt_pk_bf16_f32 v210, v216, v217
	v_cvt_pk_bf16_f32 v211, v218, v219
	v_exp_f32_e32 v220, v220
	v_exp_f32_e32 v221, v221
	v_exp_f32_e32 v222, v222
	v_add_f32_e32 v253, v220, v221
	v_exp_f32_e32 v223, v223
	v_add_f32_e32 v253, v253, v222
	v_exp_f32_e32 v224, v224
	v_add_f32_e32 v253, v253, v223
	v_exp_f32_e32 v225, v225
	v_add_f32_e32 v253, v253, v224
	v_exp_f32_e32 v226, v226
	v_add_f32_e32 v253, v253, v225
	v_exp_f32_e32 v227, v227
	v_add_f32_e32 v253, v253, v226
	v_add_f32_e32 v253, v253, v227
	v_cvt_pk_bf16_f32 v212, v220, v221
	v_cvt_pk_bf16_f32 v213, v222, v223
	v_cvt_pk_bf16_f32 v214, v224, v225
	v_cvt_pk_bf16_f32 v215, v226, v227
	v_exp_f32_e32 v228, v228
	v_exp_f32_e32 v229, v229
	v_exp_f32_e32 v230, v230
	v_add_f32_e32 v253, v253, v228
	v_exp_f32_e32 v231, v231
	v_add_f32_e32 v253, v253, v229
	v_exp_f32_e32 v232, v232
	v_add_f32_e32 v253, v253, v230
	v_exp_f32_e32 v233, v233
	v_add_f32_e32 v253, v253, v231
	v_exp_f32_e32 v234, v234
	v_add_f32_e32 v253, v253, v232
	v_exp_f32_e32 v235, v235
	v_add_f32_e32 v253, v253, v233
	v_add_f32_e32 v253, v253, v234
	v_add_f32_e32 v253, v253, v235
	v_cvt_pk_bf16_f32 v216, v228, v229
	v_cvt_pk_bf16_f32 v217, v230, v231
	v_cvt_pk_bf16_f32 v218, v232, v233
	v_cvt_pk_bf16_f32 v219, v234, v235
	v_add_f32_e32 v252, v252, v253
	v_add_f32_e32 v196, v196, v252
	s_setprio 1
	s_waitcnt lgkmcnt(5)
	v_mfma_f32_32x32x16_bf16 v[16:31], v[152:155], v[204:207], v[16:31]
	ds_read_b128 v[244:247], v198 offset:35936
	s_waitcnt lgkmcnt(5)
	v_mfma_f32_32x32x16_bf16 v[0:15], v[156:159], v[204:207], v[0:15]
	ds_read_b128 v[248:251], v198 offset:40544
	s_waitcnt lgkmcnt(5)
	v_mfma_f32_32x32x16_bf16 v[16:31], v[160:163], v[208:211], v[16:31]
	s_waitcnt lgkmcnt(4)
	v_mfma_f32_32x32x16_bf16 v[0:15], v[164:167], v[208:211], v[0:15]
	s_waitcnt lgkmcnt(3)
	v_mfma_f32_32x32x16_bf16 v[16:31], v[236:239], v[212:215], v[16:31]
	s_waitcnt lgkmcnt(2)
	v_mfma_f32_32x32x16_bf16 v[0:15], v[240:243], v[212:215], v[0:15]
	s_waitcnt lgkmcnt(1)
	v_mfma_f32_32x32x16_bf16 v[16:31], v[244:247], v[216:219], v[16:31]
	s_waitcnt lgkmcnt(0)
	v_mfma_f32_32x32x16_bf16 v[0:15], v[248:251], v[216:219], v[0:15]
	s_setprio 0
	s_branch .LBB0_1667

; template <int DQK, int DV, int MODE, int QPRE, bool DIFF> ...
;     ...
;             if (!QKFIRST) {
;                 const LAS unsigned char* kb = lds + bi * BUF + l32 * KST + hi * 16;
;             {
;                 const bf16x8 a0 = *(const LAS bf16x8*)(kb), a1 = *(const LAS bf16x8*)(kb + 32 * KST);
;                 if (MODE == 1) { const f32x16 z16 = {0.f, 0.f, 0.f, 0.f, 0.f, 0.f, 0.f, 0.f, 0.f, 0.f, 0.f, 0.f, 0.f, 0.f, 0.f, 0.f};
;                     s0 = __builtin_amdgcn_mfma_f32_32x32x16_bf16(a0, qf[0], z16, 0, 0, 0); s1 = __builtin_amdgcn_mfma_f32_32x32x16_bf16(a1, qf[0], z16, 0, 0, 0); }
;                 else { s0 = __builtin_amdgcn_mfma_f32_32x32x16_bf16(a0, qf[0], negm, 0, 0, 0); s1 = __builtin_amdgcn_mfma_f32_32x32x16_bf16(a1, qf[0], negm, 0, 0, 0); }
;             }
; #pragma unroll
;             for (int d0 = 1; d0 < ND0; ++d0) {
;                 const bf16x8 a0 = *(const LAS bf16x8*)(kb + d0 * 32), a1 = *(const LAS bf16x8*)(kb + 32 * KST + d0 * 32);
;                 s0 = __builtin_amdgcn_mfma_f32_32x32x16_bf16(a0, qf[d0], s0, 0, 0, 0);
;                 s1 = __builtin_amdgcn_mfma_f32_32x32x16_bf16(a1, qf[d0], s1, 0, 0, 0);
;             }
;             }
;             bf16x8 vf[2][4];
;     ...
;             ATT_LOADV(vf[0], 0); if (!DEEP) ATT_LOADV(vf[1], 1);
;             __builtin_amdgcn_sched_barrier(0);
;             if (MODE != 1) {
;                 float mx = fmaxf(s0[0], s1[0]);
; #pragma unroll
;                 for (int r = 1; r < 16; ++r) mx = fmaxf(fmaxf(mx, s0[r]), s1[r]);
;                 { float a, b; swap32(mx, a, b); mx = fmaxf(a, b); }
;                 const bool first = (i == 0);
;                 if (first || __any(mx > 8.0f)) {
;                     const float dl = first ? mx : fmaxf(mx, 0.f);
;                     mhat += dl;
; #pragma unroll
;                     for (int r = 0; r < 16; ++r) { s0[r] -= dl; s1[r] -= dl; negm[r] = -mhat; }
;                     if (DEEP && QKFIRST && hf == 0 && (ATT_TILE(i0 + UNR - 1) <= my_last)) {
; #pragma unroll
;                         for (int r = 0; r < 16; ++r) { sq[UNR - 1][0][r] -= dl; sq[UNR - 1][1][r] -= dl; }
;                     }
;                     if (!first) {
;                         const float alpha = __builtin_amdgcn_exp2f(-dl);
;                         l_run *= alpha;
; #pragma unroll
;                         for (int i2 = 0; i2 < NDB; ++i2)
; #pragma unroll
.Lmla_pair1:
	ds_read_b128 v[152:155], v195 offset:45056
	ds_read_b128 v[156:159], v195 offset:51712
	ds_read_b128 v[160:163], v195 offset:45088
	ds_read_b128 v[164:167], v195 offset:51744
	ds_read_b128 v[236:239], v195 offset:45120
	ds_read_b128 v[240:243], v195 offset:51776
	s_setprio 1
	s_waitcnt lgkmcnt(5)
	v_mfma_f32_32x32x16_bf16 v[48:63], v[152:155], v[128:131], v[32:47]
	ds_read_b128 v[244:247], v195 offset:45152
	s_waitcnt lgkmcnt(5)
	v_mfma_f32_32x32x16_bf16 v[64:79], v[156:159], v[128:131], v[32:47]
	ds_read_b128 v[248:251], v195 offset:51808
	s_waitcnt lgkmcnt(5)
	v_mfma_f32_32x32x16_bf16 v[48:63], v[160:163], v[132:135], v[48:63]
	ds_read_b128 v[152:155], v195 offset:45184
	s_waitcnt lgkmcnt(5)
	v_mfma_f32_32x32x16_bf16 v[64:79], v[164:167], v[132:135], v[64:79]
	ds_read_b128 v[156:159], v195 offset:51840
	s_waitcnt lgkmcnt(5)
	v_mfma_f32_32x32x16_bf16 v[48:63], v[236:239], v[136:139], v[48:63]
	ds_read_b128 v[160:163], v195 offset:45216
	s_waitcnt lgkmcnt(5)
	v_mfma_f32_32x32x16_bf16 v[64:79], v[240:243], v[136:139], v[64:79]
	ds_read_b128 v[164:167], v195 offset:51872
	s_waitcnt lgkmcnt(5)
	v_mfma_f32_32x32x16_bf16 v[48:63], v[244:247], v[140:143], v[48:63]
	ds_read_b128 v[236:239], v198 offset:58368
	s_waitcnt lgkmcnt(5)
	v_mfma_f32_32x32x16_bf16 v[64:79], v[248:251], v[140:143], v[64:79]
	ds_read_b128 v[240:243], v198 offset:62976
	s_waitcnt lgkmcnt(5)
	v_mfma_f32_32x32x16_bf16 v[48:63], v[152:155], v[144:147], v[48:63]
	ds_read_b128 v[244:247], v198 offset:58400
	s_waitcnt lgkmcnt(5)
	v_mfma_f32_32x32x16_bf16 v[64:79], v[156:159], v[144:147], v[64:79]
	ds_read_b128 v[248:251], v198 offset:63008
	s_waitcnt lgkmcnt(5)
	v_mfma_f32_32x32x16_bf16 v[48:63], v[160:163], v[148:151], v[48:63]
	ds_read_b128 v[152:155], v198 offset:58432
	s_waitcnt lgkmcnt(5)
	v_mfma_f32_32x32x16_bf16 v[64:79], v[164:167], v[148:151], v[64:79]
	ds_read_b128 v[156:159], v198 offset:63040
	s_setprio 0
	s_nop 6
	v_max3_f32 v199, v48, v49, v50
	s_nop 1
	v_max3_f32 v252, v64, v65, v66
	v_max3_f32 v199, v199, v51, v52
	v_max3_f32 v252, v252, v67, v68
	v_max3_f32 v199, v199, v53, v54
	v_max3_f32 v252, v252, v69, v70
	v_max3_f32 v199, v199, v55, v56
	v_max3_f32 v252, v252, v71, v72
	v_max3_f32 v199, v199, v57, v58
	v_max3_f32 v252, v252, v73, v74
	v_max3_f32 v199, v199, v59, v60
	v_max3_f32 v252, v252, v75, v76
	v_max3_f32 v199, v199, v61, v62
	v_max3_f32 v252, v252, v77, v78
	v_max3_f32 v199, v199, v63, v79
	v_max_f32_e32 v199, v199, v252
	v_mov_b32_e32 v252, v199
	s_nop 1
	v_permlane32_swap_b32_e32 v199, v252
	v_max_f32_e32 v199, v199, v252
	v_cmp_lt_f32_e32 vcc, s51, v199
	s_cbranch_vccnz .Lmla_rare1a
.Lmla_back1a:
	v_exp_f32_e32 v48, v48
	v_exp_f32_e32 v49, v49
	v_exp_f32_e32 v50, v50
	v_add_f32_e32 v252, v48, v49
	v_exp_f32_e32 v51, v51
	v_add_f32_e32 v252, v252, v50
	v_exp_f32_e32 v52, v52
	v_add_f32_e32 v252, v252, v51
	v_exp_f32_e32 v53, v53
	v_add_f32_e32 v252, v252, v52
	v_exp_f32_e32 v54, v54
	v_add_f32_e32 v252, v252, v53
	v_exp_f32_e32 v55, v55
	v_add_f32_e32 v252, v252, v54
	v_add_f32_e32 v252, v252, v55
	v_cvt_pk_bf16_f32 v48, v48, v49
	v_cvt_pk_bf16_f32 v49, v50, v51
	v_cvt_pk_bf16_f32 v50, v52, v53
	v_cvt_pk_bf16_f32 v51, v54, v55
	v_exp_f32_e32 v56, v56
	v_exp_f32_e32 v57, v57
	v_exp_f32_e32 v58, v58
	v_add_f32_e32 v252, v252, v56
	v_exp_f32_e32 v59, v59
	v_add_f32_e32 v252, v252, v57
	v_exp_f32_e32 v60, v60
	v_add_f32_e32 v252, v252, v58
	v_exp_f32_e32 v61, v61
	v_add_f32_e32 v252, v252, v59
	v_exp_f32_e32 v62, v62
	v_add_f32_e32 v252, v252, v60
	v_exp_f32_e32 v63, v63
	v_add_f32_e32 v252, v252, v61
	v_add_f32_e32 v252, v252, v62
	v_add_f32_e32 v252, v252, v63
	v_cvt_pk_bf16_f32 v52, v56, v57
	v_cvt_pk_bf16_f32 v53, v58, v59
	v_cvt_pk_bf16_f32 v54, v60, v61
	v_cvt_pk_bf16_f32 v55, v62, v63
	v_exp_f32_e32 v64, v64
	v_exp_f32_e32 v65, v65
	v_exp_f32_e32 v66, v66
	v_add_f32_e32 v253, v64, v65
	v_exp_f32_e32 v67, v67
	v_add_f32_e32 v253, v253, v66
	v_exp_f32_e32 v68, v68
	v_add_f32_e32 v253, v253, v67
	v_exp_f32_e32 v69, v69
	v_add_f32_e32 v253, v253, v68
	v_exp_f32_e32 v70, v70
	v_add_f32_e32 v253, v253, v69
	v_exp_f32_e32 v71, v71
	v_add_f32_e32 v253, v253, v70
	v_add_f32_e32 v253, v253, v71
	v_cvt_pk_bf16_f32 v56, v64, v65
	v_cvt_pk_bf16_f32 v57, v66, v67
	v_cvt_pk_bf16_f32 v58, v68, v69
	v_cvt_pk_bf16_f32 v59, v70, v71
	v_exp_f32_e32 v72, v72
	v_exp_f32_e32 v73, v73
	v_exp_f32_e32 v74, v74
	v_add_f32_e32 v253, v253, v72
	v_exp_f32_e32 v75, v75
	v_add_f32_e32 v253, v253, v73
	v_exp_f32_e32 v76, v76
	v_add_f32_e32 v253, v253, v74
	v_exp_f32_e32 v77, v77
	v_add_f32_e32 v253, v253, v75
	v_exp_f32_e32 v78, v78
	v_add_f32_e32 v253, v253, v76
	v_exp_f32_e32 v79, v79
	v_add_f32_e32 v253, v253, v77
	v_add_f32_e32 v253, v253, v78
	v_add_f32_e32 v253, v253, v79
	v_cvt_pk_bf16_f32 v60, v72, v73
	v_cvt_pk_bf16_f32 v61, v74, v75
	v_cvt_pk_bf16_f32 v62, v76, v77
	v_cvt_pk_bf16_f32 v63, v78, v79
	v_add_f32_e32 v252, v252, v253
	v_add_f32_e32 v196, v196, v252
	s_setprio 1
	s_waitcnt lgkmcnt(5)
	v_mfma_f32_32x32x16_bf16 v[16:31], v[236:239], v[48:51], v[16:31]
	ds_read_b128 v[160:163], v198 offset:58464
	s_waitcnt lgkmcnt(5)
	v_mfma_f32_32x32x16_bf16 v[0:15], v[240:243], v[48:51], v[0:15]
	ds_read_b128 v[164:167], v198 offset:63072
	s_waitcnt lgkmcnt(5)
	v_mfma_f32_32x32x16_bf16 v[16:31], v[244:247], v[52:55], v[16:31]
	ds_read_b128 v[236:239], v194
	s_waitcnt lgkmcnt(5)
	v_mfma_f32_32x32x16_bf16 v[0:15], v[248:251], v[52:55], v[0:15]
	ds_read_b128 v[240:243], v194 offset:6656
	s_waitcnt lgkmcnt(5)
	v_mfma_f32_32x32x16_bf16 v[16:31], v[152:155], v[56:59], v[16:31]
	ds_read_b128 v[244:247], v194 offset:32
	s_waitcnt lgkmcnt(5)
; template <int DQK, int DV, int MODE, int QPRE, bool DIFF> ...
;     ...
;             if (!QKFIRST) {
;                 const LAS unsigned char* kb = lds + bi * BUF + l32 * KST + hi * 16;
;             {
;                 const bf16x8 a0 = *(const LAS bf16x8*)(kb), a1 = *(const LAS bf16x8*)(kb + 32 * KST);
;                 if (MODE == 1) { const f32x16 z16 = {0.f, 0.f, 0.f, 0.f, 0.f, 0.f, 0.f, 0.f, 0.f, 0.f, 0.f, 0.f, 0.f, 0.f, 0.f, 0.f};
;                     s0 = __builtin_amdgcn_mfma_f32_32x32x16_bf16(a0, qf[0], z16, 0, 0, 0); s1 = __builtin_amdgcn_mfma_f32_32x32x16_bf16(a1, qf[0], z16, 0, 0, 0); }
;                 else { s0 = __builtin_amdgcn_mfma_f32_32x32x16_bf16(a0, qf[0], negm, 0, 0, 0); s1 = __builtin_amdgcn_mfma_f32_32x32x16_bf16(a1, qf[0], negm, 0, 0, 0); }
;             }
; #pragma unroll
;             for (int d0 = 1; d0 < ND0; ++d0) {
;                 const bf16x8 a0 = *(const LAS bf16x8*)(kb + d0 * 32), a1 = *(const LAS bf16x8*)(kb + 32 * KST + d0 * 32);
;                 s0 = __builtin_amdgcn_mfma_f32_32x32x16_bf16(a0, qf[d0], s0, 0, 0, 0);
;                 s1 = __builtin_amdgcn_mfma_f32_32x32x16_bf16(a1, qf[d0], s1, 0, 0, 0);
;             }
;             }
;             bf16x8 vf[2][4];
;     ...
;             ATT_LOADV(vf[0], 0); if (!DEEP) ATT_LOADV(vf[1], 1);
;             __builtin_amdgcn_sched_barrier(0);
;             if (MODE != 1) {
;                 float mx = fmaxf(s0[0], s1[0]);
; #pragma unroll
;                 for (int r = 1; r < 16; ++r) mx = fmaxf(fmaxf(mx, s0[r]), s1[r]);
;                 { float a, b; swap32(mx, a, b); mx = fmaxf(a, b); }
;                 const bool first = (i == 0);
;                 if (first || __any(mx > 8.0f)) {
;                     const float dl = first ? mx : fmaxf(mx, 0.f);
;                     mhat += dl;
; #pragma unroll
;                     for (int r = 0; r < 16; ++r) { s0[r] -= dl; s1[r] -= dl; negm[r] = -mhat; }
;                     if (DEEP && QKFIRST && hf == 0 && (ATT_TILE(i0 + UNR - 1) <= my_last)) {
; #pragma unroll
;                         for (int r = 0; r < 16; ++r) { sq[UNR - 1][0][r] -= dl; sq[UNR - 1][1][r] -= dl; }
;                     }
;                     if (!first) {
;                         const float alpha = __builtin_amdgcn_exp2f(-dl);
;                         l_run *= alpha;
; #pragma unroll
;                         for (int i2 = 0; i2 < NDB; ++i2)
; #pragma unroll
	v_mfma_f32_32x32x16_bf16 v[0:15], v[156:159], v[56:59], v[0:15]
	ds_read_b128 v[248:251], v194 offset:6688
	s_waitcnt lgkmcnt(5)
	v_mfma_f32_32x32x16_bf16 v[16:31], v[160:163], v[60:63], v[16:31]
	ds_read_b128 v[152:155], v194 offset:64
	s_waitcnt lgkmcnt(5)
	v_mfma_f32_32x32x16_bf16 v[0:15], v[164:167], v[60:63], v[0:15]
	ds_read_b128 v[156:159], v194 offset:6720
	s_waitcnt lgkmcnt(5)
	v_mfma_f32_32x32x16_bf16 v[204:219], v[236:239], v[128:131], v[32:47]
	ds_read_b128 v[160:163], v194 offset:96
	s_waitcnt lgkmcnt(5)
	v_mfma_f32_32x32x16_bf16 v[220:235], v[240:243], v[128:131], v[32:47]
	ds_read_b128 v[164:167], v194 offset:6752
	s_waitcnt lgkmcnt(5)
	v_mfma_f32_32x32x16_bf16 v[204:219], v[244:247], v[132:135], v[204:219]
	ds_read_b128 v[236:239], v194 offset:128
	s_waitcnt lgkmcnt(5)
	v_mfma_f32_32x32x16_bf16 v[220:235], v[248:251], v[132:135], v[220:235]
	ds_read_b128 v[240:243], v194 offset:6784
	s_waitcnt lgkmcnt(5)
	v_mfma_f32_32x32x16_bf16 v[204:219], v[152:155], v[136:139], v[204:219]
	ds_read_b128 v[244:247], v194 offset:160
	s_waitcnt lgkmcnt(5)
	v_mfma_f32_32x32x16_bf16 v[220:235], v[156:159], v[136:139], v[220:235]
	ds_read_b128 v[248:251], v194 offset:6816
	s_waitcnt lgkmcnt(5)
	v_mfma_f32_32x32x16_bf16 v[204:219], v[160:163], v[140:143], v[204:219]
	ds_read_b128 v[152:155], v197
	s_waitcnt lgkmcnt(5)
	v_mfma_f32_32x32x16_bf16 v[220:235], v[164:167], v[140:143], v[220:235]
	ds_read_b128 v[156:159], v197 offset:4608
	s_waitcnt lgkmcnt(5)
	v_mfma_f32_32x32x16_bf16 v[204:219], v[236:239], v[144:147], v[204:219]
	ds_read_b128 v[160:163], v197 offset:32
	s_waitcnt lgkmcnt(5)
	v_mfma_f32_32x32x16_bf16 v[220:235], v[240:243], v[144:147], v[220:235]
	ds_read_b128 v[164:167], v197 offset:4640
	s_waitcnt lgkmcnt(5)
	v_mfma_f32_32x32x16_bf16 v[204:219], v[244:247], v[148:151], v[204:219]
	ds_read_b128 v[236:239], v197 offset:64
	s_waitcnt lgkmcnt(5)
	v_mfma_f32_32x32x16_bf16 v[220:235], v[248:251], v[148:151], v[220:235]
	ds_read_b128 v[240:243], v197 offset:4672
	s_setprio 0
	s_nop 6
	v_max3_f32 v199, v204, v205, v206
	s_nop 1
	v_max3_f32 v252, v220, v221, v222
	v_max3_f32 v199, v199, v207, v208
	v_max3_f32 v252, v252, v223, v224
	v_max3_f32 v199, v199, v209, v210
	v_max3_f32 v252, v252, v225, v226
	v_max3_f32 v199, v199, v211, v212
	v_max3_f32 v252, v252, v227, v228
	v_max3_f32 v199, v199, v213, v214
	v_max3_f32 v252, v252, v229, v230
	v_max3_f32 v199, v199, v215, v216
	v_max3_f32 v252, v252, v231, v232
	v_max3_f32 v199, v199, v217, v218
	v_max3_f32 v252, v252, v233, v234
	v_max3_f32 v199, v199, v219, v235
	v_max_f32_e32 v199, v199, v252
	v_mov_b32_e32 v252, v199
	s_nop 1
	v_permlane32_swap_b32_e32 v199, v252
	v_max_f32_e32 v199, v199, v252
	v_cmp_lt_f32_e32 vcc, s51, v199
	s_cbranch_vccnz .Lmla_rare1b
.Lmla_back1b:
	v_exp_f32_e32 v204, v204
	v_exp_f32_e32 v205, v205
	v_exp_f32_e32 v206, v206
	v_add_f32_e32 v252, v204, v205
	v_exp_f32_e32 v207, v207
	v_add_f32_e32 v252, v252, v206
	v_exp_f32_e32 v208, v208
	v_add_f32_e32 v252, v252, v207
	v_exp_f32_e32 v209, v209
	v_add_f32_e32 v252, v252, v208
	v_exp_f32_e32 v210, v210
	v_add_f32_e32 v252, v252, v209
	v_exp_f32_e32 v211, v211
	v_add_f32_e32 v252, v252, v210
	v_add_f32_e32 v252, v252, v211
	v_cvt_pk_bf16_f32 v204, v204, v205
	v_cvt_pk_bf16_f32 v205, v206, v207
	v_cvt_pk_bf16_f32 v206, v208, v209
	v_cvt_pk_bf16_f32 v207, v210, v211
	v_exp_f32_e32 v212, v212
	v_exp_f32_e32 v213, v213
	v_exp_f32_e32 v214, v214
	v_add_f32_e32 v252, v252, v212
	v_exp_f32_e32 v215, v215
	v_add_f32_e32 v252, v252, v213
	v_exp_f32_e32 v216, v216
	v_add_f32_e32 v252, v252, v214
	v_exp_f32_e32 v217, v217
	v_add_f32_e32 v252, v252, v215
	v_exp_f32_e32 v218, v218
	v_add_f32_e32 v252, v252, v216
	v_exp_f32_e32 v219, v219
	v_add_f32_e32 v252, v252, v217
	v_add_f32_e32 v252, v252, v218
	v_add_f32_e32 v252, v252, v219
	v_cvt_pk_bf16_f32 v208, v212, v213
	v_cvt_pk_bf16_f32 v209, v214, v215
	v_cvt_pk_bf16_f32 v210, v216, v217
	v_cvt_pk_bf16_f32 v211, v218, v219
	v_exp_f32_e32 v220, v220
	v_exp_f32_e32 v221, v221
	v_exp_f32_e32 v222, v222
	v_add_f32_e32 v253, v220, v221
	v_exp_f32_e32 v223, v223
	v_add_f32_e32 v253, v253, v222
	v_exp_f32_e32 v224, v224
	v_add_f32_e32 v253, v253, v223
	v_exp_f32_e32 v225, v225
	v_add_f32_e32 v253, v253, v224
	v_exp_f32_e32 v226, v226
	v_add_f32_e32 v253, v253, v225
	v_exp_f32_e32 v227, v227
	v_add_f32_e32 v253, v253, v226
	v_add_f32_e32 v253, v253, v227
	v_cvt_pk_bf16_f32 v212, v220, v221
	v_cvt_pk_bf16_f32 v213, v222, v223
	v_cvt_pk_bf16_f32 v214, v224, v225
	v_cvt_pk_bf16_f32 v215, v226, v227
	v_exp_f32_e32 v228, v228
	v_exp_f32_e32 v229, v229
	v_exp_f32_e32 v230, v230
	v_add_f32_e32 v253, v253, v228
	v_exp_f32_e32 v231, v231
	v_add_f32_e32 v253, v253, v229
	v_exp_f32_e32 v232, v232
	v_add_f32_e32 v253, v253, v230
	v_exp_f32_e32 v233, v233
	v_add_f32_e32 v253, v253, v231
	v_exp_f32_e32 v234, v234
	v_add_f32_e32 v253, v253, v232
	v_exp_f32_e32 v235, v235
	v_add_f32_e32 v253, v253, v233
	v_add_f32_e32 v253, v253, v234
	v_add_f32_e32 v253, v253, v235
	v_cvt_pk_bf16_f32 v216, v228, v229
	v_cvt_pk_bf16_f32 v217, v230, v231
	v_cvt_pk_bf16_f32 v218, v232, v233
	v_cvt_pk_bf16_f32 v219, v234, v235
	v_add_f32_e32 v252, v252, v253
	v_add_f32_e32 v196, v196, v252
	s_setprio 1
	s_waitcnt lgkmcnt(5)
	v_mfma_f32_32x32x16_bf16 v[16:31], v[152:155], v[204:207], v[16:31]
	ds_read_b128 v[244:247], v197 offset:96
	s_waitcnt lgkmcnt(5)
	v_mfma_f32_32x32x16_bf16 v[0:15], v[156:159], v[204:207], v[0:15]
	ds_read_b128 v[248:251], v197 offset:4704
	s_waitcnt lgkmcnt(5)
	v_mfma_f32_32x32x16_bf16 v[16:31], v[160:163], v[208:211], v[16:31]
	s_waitcnt lgkmcnt(4)
	v_mfma_f32_32x32x16_bf16 v[0:15], v[164:167], v[208:211], v[0:15]
	s_waitcnt lgkmcnt(3)
	v_mfma_f32_32x32x16_bf16 v[16:31], v[236:239], v[212:215], v[16:31]
	s_waitcnt lgkmcnt(2)
	v_mfma_f32_32x32x16_bf16 v[0:15], v[240:243], v[212:215], v[0:15]
	s_waitcnt lgkmcnt(1)
	v_mfma_f32_32x32x16_bf16 v[16:31], v[244:247], v[216:219], v[16:31]
	s_waitcnt lgkmcnt(0)
	v_mfma_f32_32x32x16_bf16 v[0:15], v[248:251], v[216:219], v[0:15]
	s_setprio 0
	s_branch .LBB0_1701
